# v46 + layer-1 gate/up copy items [18432,22016) made by the tile-less workgroups of layer 0's gate/up tail round; no gate/up items left in the attention-phase stream
# baseline (speedup 1.0000x reference)
.Ltrn_done:
.Ltru_entry:
	v_readlane_b32 s8, v251, 48
	v_readlane_b32 s9, v251, 54
	v_readlane_b32 s34, v251, 10
	v_readlane_b32 s35, v251, 11
	v_readlane_b32 s36, v251, 24
	v_readlane_b32 s37, v251, 25
	v_readlane_b32 s6, v251, 2
	v_readlane_b32 s7, v251, 3
	s_nop 0
	s_sub_i32 s8, s8, 128
	s_lshl_b32 s8, s8, 3
	s_lshr_b32 s9, s9, 6
	s_add_i32 s8, s8, s9
	s_add_i32 s8, s8, 0x4800
	s_mul_i32 s32, s9, 0x2100
	s_add_u32 s34, s34, 0x15800000
	s_addc_u32 s35, s35, 0
	s_add_u32 s36, s36, 0x8000
	s_addc_u32 s37, s37, 0
	s_add_u32 s6, s6, 0x13800000
	s_addc_u32 s7, s7, 0
	v_mbcnt_lo_u32_b32 v32, -1, 0
	v_mbcnt_hi_u32_b32 v32, -1, v32
	v_lshrrev_b32_e32 v34, 4, v32
	v_and_b32_e32 v35, 15, v32
	v_and_b32_e32 v36, 7, v32
	v_lshrrev_b32_e32 v37, 3, v32
	v_lshlrev_b32_e32 v30, 3, v34
	v_mul_u32_u24_e32 v38, 0x2b000, v34
	v_lshl_add_u32 v38, v35, 4, v38
	v_mov_b32_e32 v0, v38
	v_add_u32_e32 v1, 0x15800, v38
	v_add_u32_e32 v2, 0xac000, v38
	v_add_u32_e32 v3, 0xc1800, v38
	v_add_u32_e32 v4, 0x158000, v38
	v_add_u32_e32 v5, 0x16d800, v38
	v_add_u32_e32 v6, 0x204000, v38
	v_add_u32_e32 v7, 0x219800, v38
	v_add_u32_e32 v8, 0x2b0000, v38
	v_add_u32_e32 v9, 0x2c5800, v38
	v_add_u32_e32 v10, 0x35c000, v38
	v_add_u32_e32 v11, 0x371800, v38
	v_add_u32_e32 v16, 0x408000, v38
	v_add_u32_e32 v17, 0x41d800, v38
	v_add_u32_e32 v18, 0x4b4000, v38
	v_add_u32_e32 v19, 0x4c9800, v38
	v_lshlrev_b32_e32 v39, 13, v37
	v_lshl_add_u32 v39, v36, 4, v39
	v_mov_b32_e32 v20, v39
	v_add_u32_e32 v21, 0x10000, v39
	v_add_u32_e32 v22, 0x20000, v39
	v_add_u32_e32 v23, 0x30000, v39
	v_add_u32_e32 v24, 0x40000, v39
	v_add_u32_e32 v25, 0x50000, v39
	v_add_u32_e32 v26, 0x60000, v39
	v_add_u32_e32 v27, 0x70000, v39
	v_mul_u32_u24_e32 v28, 0x104, v34
	v_lshl_add_u32 v28, v35, 4, v28
	v_add_u32_e32 v28, s32, v28
	v_mul_u32_u24_e32 v29, 0x410, v36
	v_lshl_add_u32 v29, v37, 2, v29
	v_add_u32_e32 v29, s32, v29
	s_cmpk_lt_i32 s8, 0x5600
	s_cbranch_scc0 .Ltru_done
	s_mul_hi_u32 s23, s8, 0x2fa0be83
	s_lshr_b32 s23, s23, 6
	s_mul_i32 s25, s23, 0x158
	s_sub_i32 s24, s8, s25
	s_mul_i32 s25, s23, 0x560000
	s_lshl_b32 s33, s24, 8
	s_add_i32 s25, s25, s33
	s_add_u32 s26, s34, s25
	s_addc_u32 s27, s35, 0
	s_lshl_b32 s25, s23, 8
	s_add_u32 s28, s36, s25
	s_addc_u32 s29, s37, 0
	global_load_dwordx4 v[44:47], v0, s[26:27]
	global_load_dwordx4 v[48:51], v1, s[26:27]
	global_load_dwordx4 v[52:55], v2, s[26:27]
	global_load_dwordx4 v[56:59], v3, s[26:27]
	global_load_dwordx4 v[60:63], v4, s[26:27]
	global_load_dwordx4 v[64:67], v5, s[26:27]
	global_load_dwordx4 v[68:71], v6, s[26:27]
	global_load_dwordx4 v[72:75], v7, s[26:27]
	global_load_dwordx4 v[76:79], v8, s[26:27]
	global_load_dwordx4 v[80:83], v9, s[26:27]
	global_load_dwordx4 v[84:87], v10, s[26:27]
	global_load_dwordx4 v[88:91], v11, s[26:27]
	global_load_dwordx4 v[92:95], v16, s[26:27]
	global_load_dwordx4 v[104:107], v17, s[26:27]
	global_load_dwordx4 v[108:111], v18, s[26:27]
	global_load_dwordx4 v[112:115], v19, s[26:27]
	global_load_dwordx2 v[116:117], v30, s[28:29]
	global_load_dwordx2 v[118:119], v30, s[28:29] offset:32
	global_load_dwordx2 v[120:121], v30, s[28:29] offset:64
	global_load_dwordx2 v[122:123], v30, s[28:29] offset:96
	global_load_dwordx2 v[124:125], v30, s[28:29] offset:128
	global_load_dwordx2 v[126:127], v30, s[28:29] offset:160
	global_load_dwordx2 v[128:129], v30, s[28:29] offset:192
	global_load_dwordx2 v[130:131], v30, s[28:29] offset:224
	s_waitcnt vmcnt(0)
	s_branch .Ltru_body

.Ltru_body:
	s_mul_hi_u32 s23, s8, 0x2fa0be83
	s_lshr_b32 s23, s23, 6
	s_mul_i32 s25, s23, 0x158
	s_sub_i32 s24, s8, s25
	s_cmpk_ge_u32 s24, 0xac
	s_cselect_b32 s25, 0xac, 0
	s_cselect_b32 s33, 0x80, 0
	s_sub_i32 s24, s24, s25
	s_and_b32 s25, s24, 1
	s_lshl_b32 s25, s25, 6
	s_lshr_b32 s24, s24, 1
	s_lshl_b32 s24, s24, 8
	s_add_i32 s24, s24, s25
	s_add_i32 s24, s24, s33
	s_lshl_b32 s24, s24, 13
	s_lshl_b32 s25, s23, 7
	s_add_i32 s24, s24, s25
	s_add_u32 s30, s6, s24
	s_addc_u32 s31, s7, 0
	v_mul_f32_e32 v34, v44, v116
	v_mul_f32_e32 v35, v48, v117
	v_cvt_pk_bf16_f32 v38, v34, v35
	ds_write_b32 v28, v38
	v_mul_f32_e32 v36, v45, v116
	v_mul_f32_e32 v37, v49, v117
	v_cvt_pk_bf16_f32 v39, v36, v37
	ds_write_b32 v28, v39 offset:4
	v_mul_f32_e32 v34, v46, v116
	v_mul_f32_e32 v35, v50, v117
	v_cvt_pk_bf16_f32 v40, v34, v35
	ds_write_b32 v28, v40 offset:8
	v_mul_f32_e32 v36, v47, v116
	v_mul_f32_e32 v37, v51, v117
	v_cvt_pk_bf16_f32 v41, v36, v37
	ds_write_b32 v28, v41 offset:12
	v_mul_f32_e32 v34, v52, v118
	v_mul_f32_e32 v35, v56, v119
	v_cvt_pk_bf16_f32 v38, v34, v35
	ds_write_b32 v28, v38 offset:1040
	v_mul_f32_e32 v36, v53, v118
	v_mul_f32_e32 v37, v57, v119
	v_cvt_pk_bf16_f32 v39, v36, v37
	ds_write_b32 v28, v39 offset:1044
	v_mul_f32_e32 v34, v54, v118
	v_mul_f32_e32 v35, v58, v119
	v_cvt_pk_bf16_f32 v40, v34, v35
	ds_write_b32 v28, v40 offset:1048
	v_mul_f32_e32 v36, v55, v118
	v_mul_f32_e32 v37, v59, v119
	v_cvt_pk_bf16_f32 v41, v36, v37
	ds_write_b32 v28, v41 offset:1052
	v_mul_f32_e32 v34, v60, v120
	v_mul_f32_e32 v35, v64, v121
	v_cvt_pk_bf16_f32 v38, v34, v35
	ds_write_b32 v28, v38 offset:2080
	v_mul_f32_e32 v36, v61, v120
	v_mul_f32_e32 v37, v65, v121
	v_cvt_pk_bf16_f32 v39, v36, v37
	ds_write_b32 v28, v39 offset:2084
	v_mul_f32_e32 v34, v62, v120
	v_mul_f32_e32 v35, v66, v121
	v_cvt_pk_bf16_f32 v40, v34, v35
	ds_write_b32 v28, v40 offset:2088
	v_mul_f32_e32 v36, v63, v120
	v_mul_f32_e32 v37, v67, v121
	v_cvt_pk_bf16_f32 v41, v36, v37
	ds_write_b32 v28, v41 offset:2092
	v_mul_f32_e32 v34, v68, v122
	v_mul_f32_e32 v35, v72, v123
	v_cvt_pk_bf16_f32 v38, v34, v35
	ds_write_b32 v28, v38 offset:3120
	v_mul_f32_e32 v36, v69, v122
	v_mul_f32_e32 v37, v73, v123
	v_cvt_pk_bf16_f32 v39, v36, v37
	ds_write_b32 v28, v39 offset:3124
	v_mul_f32_e32 v34, v70, v122
	v_mul_f32_e32 v35, v74, v123
	v_cvt_pk_bf16_f32 v40, v34, v35
	ds_write_b32 v28, v40 offset:3128
	v_mul_f32_e32 v36, v71, v122
	v_mul_f32_e32 v37, v75, v123
	v_cvt_pk_bf16_f32 v41, v36, v37
	ds_write_b32 v28, v41 offset:3132
	v_mul_f32_e32 v34, v76, v124
	v_mul_f32_e32 v35, v80, v125
	v_cvt_pk_bf16_f32 v38, v34, v35
	ds_write_b32 v28, v38 offset:4160
	v_mul_f32_e32 v36, v77, v124
	v_mul_f32_e32 v37, v81, v125
	v_cvt_pk_bf16_f32 v39, v36, v37
	ds_write_b32 v28, v39 offset:4164
	v_mul_f32_e32 v34, v78, v124
	v_mul_f32_e32 v35, v82, v125
	v_cvt_pk_bf16_f32 v40, v34, v35
	ds_write_b32 v28, v40 offset:4168
	v_mul_f32_e32 v36, v79, v124
	v_mul_f32_e32 v37, v83, v125
	v_cvt_pk_bf16_f32 v41, v36, v37
	ds_write_b32 v28, v41 offset:4172
	v_mul_f32_e32 v34, v84, v126
	v_mul_f32_e32 v35, v88, v127
	v_cvt_pk_bf16_f32 v38, v34, v35
	ds_write_b32 v28, v38 offset:5200
	v_mul_f32_e32 v36, v85, v126
	v_mul_f32_e32 v37, v89, v127
	v_cvt_pk_bf16_f32 v39, v36, v37
	ds_write_b32 v28, v39 offset:5204
	v_mul_f32_e32 v34, v86, v126
	v_mul_f32_e32 v35, v90, v127
	v_cvt_pk_bf16_f32 v40, v34, v35
	ds_write_b32 v28, v40 offset:5208
	v_mul_f32_e32 v36, v87, v126
	v_mul_f32_e32 v37, v91, v127
	v_cvt_pk_bf16_f32 v41, v36, v37
	ds_write_b32 v28, v41 offset:5212
	v_mul_f32_e32 v34, v92, v128
	v_mul_f32_e32 v35, v104, v129
	v_cvt_pk_bf16_f32 v38, v34, v35
	ds_write_b32 v28, v38 offset:6240
	v_mul_f32_e32 v36, v93, v128
	v_mul_f32_e32 v37, v105, v129
	v_cvt_pk_bf16_f32 v39, v36, v37
	ds_write_b32 v28, v39 offset:6244
	v_mul_f32_e32 v34, v94, v128
	v_mul_f32_e32 v35, v106, v129
	v_cvt_pk_bf16_f32 v40, v34, v35
	ds_write_b32 v28, v40 offset:6248
	v_mul_f32_e32 v36, v95, v128
	v_mul_f32_e32 v37, v107, v129
	v_cvt_pk_bf16_f32 v41, v36, v37
	ds_write_b32 v28, v41 offset:6252
	v_mul_f32_e32 v34, v108, v130
	v_mul_f32_e32 v35, v112, v131
	v_cvt_pk_bf16_f32 v38, v34, v35
	ds_write_b32 v28, v38 offset:7280
	v_mul_f32_e32 v36, v109, v130
	v_mul_f32_e32 v37, v113, v131
	v_cvt_pk_bf16_f32 v39, v36, v37
	ds_write_b32 v28, v39 offset:7284
	v_mul_f32_e32 v34, v110, v130
	v_mul_f32_e32 v35, v114, v131
	v_cvt_pk_bf16_f32 v40, v34, v35
	ds_write_b32 v28, v40 offset:7288
	v_mul_f32_e32 v36, v111, v130
	v_mul_f32_e32 v37, v115, v131
	v_cvt_pk_bf16_f32 v41, v36, v37
	ds_write_b32 v28, v41 offset:7292
	s_add_i32 s9, s8, 0x400
	s_cmpk_lt_i32 s9, 0x5600
	s_cbranch_scc0 .Ltru_noload
	s_mul_hi_u32 s23, s9, 0x2fa0be83
	s_lshr_b32 s23, s23, 6
	s_mul_i32 s25, s23, 0x158
	s_sub_i32 s24, s9, s25
	s_mul_i32 s25, s23, 0x560000
	s_lshl_b32 s33, s24, 8
	s_add_i32 s25, s25, s33
	s_add_u32 s26, s34, s25
	s_addc_u32 s27, s35, 0
	s_lshl_b32 s25, s23, 8
	s_add_u32 s28, s36, s25
	s_addc_u32 s29, s37, 0
	global_load_dwordx4 v[44:47], v0, s[26:27]
	global_load_dwordx4 v[48:51], v1, s[26:27]
	global_load_dwordx4 v[52:55], v2, s[26:27]
	global_load_dwordx4 v[56:59], v3, s[26:27]
	global_load_dwordx4 v[60:63], v4, s[26:27]
	global_load_dwordx4 v[64:67], v5, s[26:27]
	global_load_dwordx4 v[68:71], v6, s[26:27]
	global_load_dwordx4 v[72:75], v7, s[26:27]
	global_load_dwordx4 v[76:79], v8, s[26:27]
	global_load_dwordx4 v[80:83], v9, s[26:27]
	global_load_dwordx4 v[84:87], v10, s[26:27]
	global_load_dwordx4 v[88:91], v11, s[26:27]
	global_load_dwordx4 v[92:95], v16, s[26:27]
	global_load_dwordx4 v[104:107], v17, s[26:27]
	global_load_dwordx4 v[108:111], v18, s[26:27]
	global_load_dwordx4 v[112:115], v19, s[26:27]
	global_load_dwordx2 v[116:117], v30, s[28:29]
	global_load_dwordx2 v[118:119], v30, s[28:29] offset:32
	global_load_dwordx2 v[120:121], v30, s[28:29] offset:64
	global_load_dwordx2 v[122:123], v30, s[28:29] offset:96
	global_load_dwordx2 v[124:125], v30, s[28:29] offset:128
	global_load_dwordx2 v[126:127], v30, s[28:29] offset:160
	global_load_dwordx2 v[128:129], v30, s[28:29] offset:192
	global_load_dwordx2 v[130:131], v30, s[28:29] offset:224
.Ltru_noload:
	s_waitcnt lgkmcnt(0)
	ds_read2_b32 v[180:181], v29 offset0:0 offset1:65
	ds_read2_b32 v[182:183], v29 offset0:130 offset1:195
	ds_read2_b32 v[188:189], v29 offset0:8 offset1:73
	ds_read2_b32 v[190:191], v29 offset0:138 offset1:203
	ds_read2_b32 v[196:197], v29 offset0:16 offset1:81
	ds_read2_b32 v[198:199], v29 offset0:146 offset1:211
	ds_read2_b32 v[200:201], v29 offset0:24 offset1:89
	ds_read2_b32 v[202:203], v29 offset0:154 offset1:219
	ds_read2_b32 v[204:205], v29 offset0:32 offset1:97
	ds_read2_b32 v[206:207], v29 offset0:162 offset1:227
	ds_read2_b32 v[232:233], v29 offset0:40 offset1:105
	ds_read2_b32 v[234:235], v29 offset0:170 offset1:235
	ds_read2_b32 v[236:237], v29 offset0:48 offset1:113
	ds_read2_b32 v[238:239], v29 offset0:178 offset1:243
	ds_read2_b32 v[240:241], v29 offset0:56 offset1:121
	ds_read2_b32 v[242:243], v29 offset0:186 offset1:251
	s_waitcnt lgkmcnt(0)
	global_store_dwordx4 v20, v[180:183], s[30:31]
	global_store_dwordx4 v21, v[188:191], s[30:31]
	global_store_dwordx4 v22, v[196:199], s[30:31]
	global_store_dwordx4 v23, v[200:203], s[30:31]
	global_store_dwordx4 v24, v[204:207], s[30:31]
	global_store_dwordx4 v25, v[232:235], s[30:31]
	global_store_dwordx4 v26, v[236:239], s[30:31]
	global_store_dwordx4 v27, v[240:243], s[30:31]
	s_mov_b32 s8, s9
	s_cmpk_lt_i32 s8, 0x5600
	s_cbranch_scc1 .Ltru_loop
.Ltru_done:
.LBB0_2224:
	v_readlane_b32 s4, v254, 40
	s_add_i32 s22, s4, 13
	s_cmp_ge_i32 s22, s65
	s_cbranch_scc1 .LBB0_2273
	s_waitcnt vmcnt(0)
	s_waitcnt vmcnt(0) lgkmcnt(0)
	s_barrier
	s_mov_b64 s[4:5], exec
	v_readlane_b32 s6, v253, 27
	v_readlane_b32 s7, v253, 28
	s_and_b64 s[6:7], s[4:5], s[6:7]
	s_mov_b64 exec, s[6:7]
	s_cbranch_execz .LBB0_2272
	v_mov_b32_e32 v0, s79
	s_waitcnt vmcnt(0) expcnt(0) lgkmcnt(0)
	ds_read_b32 v2, v0
	ds_read_b32 v0, v0 offset:4
	s_waitcnt lgkmcnt(1)
	v_cmp_ne_u32_e32 vcc, 0, v2
	s_cbranch_vccnz .LBB0_2240
	v_readlane_b32 s8, v251, 0
	v_readlane_b32 s9, v251, 1
	s_load_dwordx2 s[6:7], s[8:9], 0x4
	s_mov_b32 s14, 0
	s_waitcnt lgkmcnt(0)
	s_mul_i32 s13, s6, s97
	s_mul_i32 s13, s13, s7
	s_branch .LBB0_2229
